# P4 publish path: half-tile totals written to LDS with ds_write2_b32 (no copies); per-column products after the flag update as single v_mul_f32
# baseline (speedup 1.0000x reference)
.LBB0_464:
	s_lshl_b32 s6, s62, 7
	v_mov_b32_e32 v239, v224
	v_mov_b32_e32 v237, v225
	s_or_b32 s6, s6, s96
	s_nop 0
	v_lshl_add_u32 v238, v237, 3, s6
	s_lshl_b32 s6, s63, 8
	s_add_i32 s6, s6, s16
	v_lshl_add_u32 v171, v239, 3, s6
	v_lshlrev_b32_e32 v232, 1, v238
	v_lshlrev_b32_e32 v233, 11, v171
	v_lshlrev_b32_e32 v92, 2, v238
	v_add_u32_e32 v164, v233, v232
	v_or_b32_e32 v235, 0x1000, v233
	global_load_dwordx4 v[184:187], v92, s[2:3] offset:16
	global_load_dwordx4 v[188:191], v92, s[2:3]
	global_load_dwordx4 v[192:195], v92, s[12:13] offset:16
	global_load_dwordx4 v[196:199], v92, s[12:13]
	global_load_dwordx4 v[240:243], v92, s[36:37] offset:16
	global_load_dwordx4 v[200:203], v92, s[36:37]
	v_or_b32_e32 v234, 0x800, v233
	v_add_u32_e32 v180, v235, v232
	v_or_b32_e32 v236, 0x1800, v233
	v_add_u32_e32 v176, 0x2000, v164
	v_add_u32_e32 v172, 0x3000, v164
	v_add_u32_e32 v182, v234, v232
	global_load_dwordx4 v[244:247], v164, s[26:27]
	global_load_dwordx4 v[152:155], v182, s[26:27]
	v_add_u32_e32 v178, v236, v232
	global_load_dwordx4 v[148:151], v180, s[26:27]
	global_load_dwordx4 v[144:147], v178, s[26:27]
	v_add_u32_e32 v174, 0x2800, v164
	global_load_dwordx4 v[140:143], v176, s[26:27]
	global_load_dwordx4 v[132:135], v174, s[26:27]
	v_add_u32_e32 v170, 0x3800, v164
	global_load_dwordx4 v[112:115], v172, s[26:27]
	global_load_dwordx4 v[92:95], v170, s[26:27]
	v_and_b32_e32 v171, 0x1ff8, v171
	s_waitcnt vmcnt(0)
	v_pk_mul_f32 v[204:205], v[186:187], s[48:49] op_sel_hi:[1,0]
	v_pk_mul_f32 v[216:217], v[190:191], s[48:49] op_sel_hi:[1,0]
	v_pk_mul_f32 v[222:223], v[188:189], s[48:49] op_sel_hi:[1,0]
	v_pk_mul_f32 v[214:215], v[198:199], s[48:49] op_sel_hi:[1,0]
	v_pk_mul_f32 v[220:221], v[196:197], s[48:49] op_sel_hi:[1,0]
	v_pk_mul_f32 v[212:213], v[202:203], s[50:51] op_sel_hi:[1,0]
	v_pk_mul_f32 v[218:219], v[200:201], s[50:51] op_sel_hi:[1,0]
	v_pk_mul_f32 v[202:203], v[194:195], s[48:49] op_sel_hi:[1,0]
	v_pk_mul_f32 v[200:201], v[242:243], s[50:51] op_sel_hi:[1,0]
	v_pk_mul_f32 v[210:211], v[184:185], s[48:49] op_sel_hi:[1,0]
	v_pk_mul_f32 v[208:209], v[192:193], s[48:49] op_sel_hi:[1,0]
	v_pk_mul_f32 v[206:207], v[240:241], s[50:51] op_sel_hi:[1,0]
	v_fmamk_f32 v136, v136, 0xbfb8aa3b, v222
	v_exp_f32_e32 v136, v136
	v_fmamk_f32 v128, v128, 0xbfb8aa3b, v220
	v_fmamk_f32 v137, v137, 0xbfb8aa3b, v223
	v_exp_f32_e32 v128, v128
	v_add_f32_e32 v136, 1.0, v136
	v_rcp_f32_e32 v136, v136
	v_exp_f32_e32 v137, v137
	v_add_f32_e32 v128, 1.0, v128
	v_rcp_f32_e32 v128, v128
	v_mul_f32_e32 v136, v218, v136
	v_exp_f32_e32 v136, v136
	v_add_f32_e32 v137, 1.0, v137
	v_rcp_f32_e32 v175, v137
	v_cmp_eq_u32_e32 vcc, 0, v171
	v_fma_f32 v173, -v136, v136, 1.0
	v_sqrt_f32_e32 v173, v173
	v_fmamk_f32 v129, v129, 0xbfb8aa3b, v221
	v_exp_f32_e32 v129, v129
	v_lshlrev_b32_e32 v185, 16, v244
	v_cndmask_b32_e64 v137, v173, 1.0, vcc
	v_mul_f32_e32 v137, v128, v137
	v_mul_f32_e32 v128, v219, v175
	v_exp_f32_e32 v128, v128
	v_and_b32_e32 v187, 0xffff0000, v244
	v_mov_b32_e32 v184, v165
	v_mul_f32_e32 v186, v137, v185
	v_fma_f32 v171, -v128, v128, 1.0
	v_sqrt_f32_e32 v171, v171
	v_add_f32_e32 v129, 1.0, v129
	v_fmamk_f32 v138, v138, 0xbfb8aa3b, v216
	v_pk_fma_f32 v[184:185], v[136:137], v[184:185], v[186:187] op_sel_hi:[1,1,0]
	v_rcp_f32_e32 v129, v129
	v_cndmask_b32_e64 v137, v171, 1.0, vcc
	v_exp_f32_e32 v171, v138
	v_fmamk_f32 v130, v130, 0xbfb8aa3b, v214
	v_mul_f32_e32 v129, v129, v137
	v_exp_f32_e32 v130, v130
	v_add_f32_e32 v137, 1.0, v171
	v_rcp_f32_e32 v137, v137
	v_mov_b32_e32 v186, v165
	v_mul_f32_e32 v138, v129, v187
	v_pk_fma_f32 v[186:187], v[128:129], v[186:187], v[138:139] op_sel_hi:[1,1,0]
	v_mul_f32_e32 v129, v212, v137
	v_exp_f32_e32 v138, v129
	v_add_f32_e32 v129, 1.0, v130
	v_fmamk_f32 v130, v139, 0xbfb8aa3b, v217
	v_exp_f32_e32 v130, v130
	v_fma_f32 v137, -v138, v138, 1.0
	v_sqrt_f32_e32 v137, v137
	v_rcp_f32_e32 v129, v129
	v_add_f32_e32 v130, 1.0, v130
	v_rcp_f32_e32 v130, v130
	v_cndmask_b32_e64 v137, v137, 1.0, vcc
	v_mul_f32_e32 v139, v129, v137
	v_fmamk_f32 v124, v124, 0xbfb8aa3b, v210
	v_mul_f32_e32 v129, v213, v130
	v_exp_f32_e32 v130, v129
	v_fmamk_f32 v129, v131, 0xbfb8aa3b, v215
	v_exp_f32_e32 v129, v129
	v_exp_f32_e32 v137, v124
	v_fma_f32 v131, -v130, v130, 1.0
	v_sqrt_f32_e32 v131, v131
	v_add_f32_e32 v129, 1.0, v129
	v_rcp_f32_e32 v129, v129
	v_lshlrev_b32_e32 v189, 16, v245
	v_cndmask_b32_e64 v131, v131, 1.0, vcc
	v_and_b32_e32 v191, 0xffff0000, v245
	v_mul_f32_e32 v131, v129, v131
	v_add_f32_e32 v129, 1.0, v137
	v_rcp_f32_e32 v129, v129
	v_mov_b32_e32 v188, v165
	v_mul_f32_e32 v190, v139, v189
	v_pk_fma_f32 v[188:189], v[138:139], v[188:189], v[190:191] op_sel_hi:[1,1,0]
	v_mov_b32_e32 v190, v165
	v_mul_f32_e32 v124, v131, v191
	v_pk_fma_f32 v[190:191], v[130:131], v[190:191], v[124:125] op_sel_hi:[1,1,0]
	v_mul_f32_e32 v124, v206, v129
	v_fmamk_f32 v120, v120, 0xbfb8aa3b, v208
	v_exp_f32_e32 v124, v124
	v_fmamk_f32 v125, v125, 0xbfb8aa3b, v211
	v_exp_f32_e32 v120, v120
	v_exp_f32_e32 v125, v125
	v_fma_f32 v129, -v124, v124, 1.0
	v_sqrt_f32_e32 v129, v129
	v_add_f32_e32 v120, 1.0, v120
	v_add_f32_e32 v125, 1.0, v125
	v_rcp_f32_e32 v120, v120
	v_rcp_f32_e32 v131, v125
	v_cndmask_b32_e64 v125, v129, 1.0, vcc
	v_fmamk_f32 v121, v121, 0xbfb8aa3b, v209
	v_mul_f32_e32 v125, v120, v125
	v_mul_f32_e32 v120, v207, v131
	v_exp_f32_e32 v120, v120
	v_exp_f32_e32 v121, v121
	v_lshlrev_b32_e32 v193, 16, v246
	v_and_b32_e32 v195, 0xffff0000, v246
	v_fma_f32 v129, -v120, v120, 1.0
	v_sqrt_f32_e32 v129, v129
	v_mov_b32_e32 v192, v165
	v_mul_f32_e32 v194, v125, v193
	v_add_f32_e32 v121, 1.0, v121
	v_fmamk_f32 v126, v126, 0xbfb8aa3b, v204
	v_pk_fma_f32 v[192:193], v[124:125], v[192:193], v[194:195] op_sel_hi:[1,1,0]
	v_rcp_f32_e32 v121, v121
	v_cndmask_b32_e64 v125, v129, 1.0, vcc
	v_exp_f32_e32 v129, v126
	v_mov_b32_e32 v194, v165
	v_mul_f32_e32 v121, v121, v125
	v_mul_f32_e32 v126, v121, v195
	v_add_f32_e32 v125, 1.0, v129
	v_rcp_f32_e32 v125, v125
	v_pk_fma_f32 v[194:195], v[120:121], v[194:195], v[126:127] op_sel_hi:[1,1,0]
	v_fmamk_f32 v122, v122, 0xbfb8aa3b, v202
	v_exp_f32_e32 v129, v122
	v_mul_f32_e32 v121, v200, v125
	v_fmamk_f32 v125, v127, 0xbfb8aa3b, v205
	v_exp_f32_e32 v125, v125
	v_exp_f32_e32 v122, v121
	v_fmamk_f32 v123, v123, 0xbfb8aa3b, v203
	v_add_f32_e32 v121, 1.0, v129
	v_add_f32_e32 v125, 1.0, v125
	v_fma_f32 v126, -v122, v122, 1.0
	v_rcp_f32_e32 v125, v125
	v_sqrt_f32_e32 v126, v126
	v_exp_f32_e32 v129, v123
	v_rcp_f32_e32 v121, v121
	v_mul_f32_e32 v123, v201, v125
	v_cndmask_b32_e64 v127, v126, 1.0, vcc
	v_exp_f32_e32 v126, v123
	v_mul_f32_e32 v123, v121, v127
	v_add_f32_e32 v121, 1.0, v129
	v_rcp_f32_e32 v121, v121
	v_fma_f32 v125, -v126, v126, 1.0
	v_sqrt_f32_e32 v125, v125
	v_lshlrev_b32_e32 v197, 16, v247
	v_and_b32_e32 v199, 0xffff0000, v247
	v_mov_b32_e32 v196, v165
	v_mul_f32_e32 v198, v123, v197
	v_pk_fma_f32 v[196:197], v[122:123], v[196:197], v[198:199] op_sel_hi:[1,1,0]
	v_cndmask_b32_e64 v123, v125, 1.0, vcc
	v_mul_f32_e32 v127, v121, v123
	v_mov_b32_e32 v198, v165
	v_mul_f32_e32 v240, v127, v199
	v_pk_fma_f32 v[198:199], v[126:127], v[198:199], v[240:241] op_sel_hi:[1,1,0]
	v_fmamk_f32 v116, v116, 0xbfb8aa3b, v222
	v_exp_f32_e32 v116, v116
	v_fmamk_f32 v108, v108, 0xbfb8aa3b, v220
	v_exp_f32_e32 v108, v108
	v_fmamk_f32 v117, v117, 0xbfb8aa3b, v223
	v_add_f32_e32 v116, 1.0, v116
	v_rcp_f32_e32 v116, v116
	v_add_f32_e32 v108, 1.0, v108
	v_rcp_f32_e32 v108, v108
	v_exp_f32_e32 v121, v117
	v_mul_f32_e32 v116, v218, v116
	v_exp_f32_e32 v241, v116
	v_fmamk_f32 v109, v109, 0xbfb8aa3b, v221
	v_exp_f32_e32 v123, v109
	v_lshlrev_b32_e32 v242, 16, v153
	v_fma_f32 v116, -v241, v241, 1.0
	v_sqrt_f32_e32 v116, v116
	v_and_b32_e32 v244, 0xffff0000, v153
	v_lshlrev_b32_e32 v240, 16, v152
	v_mov_b32_e32 v117, v184
	v_mul_f32_e32 v116, v108, v116
	v_add_f32_e32 v108, 1.0, v121
	v_rcp_f32_e32 v121, v108
	v_mul_f32_e32 v108, v184, v241
	v_fmamk_f32 v110, v110, 0xbfb8aa3b, v214
	v_exp_f32_e32 v110, v110
	v_mul_f32_e32 v109, v219, v121
	v_exp_f32_e32 v153, v109
	v_pk_fma_f32 v[108:109], v[116:117], v[240:241], v[108:109] op_sel_hi:[1,1,0]
	v_and_b32_e32 v152, 0xffff0000, v152
	v_add_f32_e32 v109, 1.0, v123
	v_rcp_f32_e32 v116, v109
	v_fma_f32 v109, -v153, v153, 1.0
	v_sqrt_f32_e32 v117, v109
	v_fmamk_f32 v109, v118, 0xbfb8aa3b, v216
	v_exp_f32_e32 v118, v109
	v_add_f32_e32 v110, 1.0, v110
	v_mul_f32_e32 v116, v116, v117
	v_mov_b32_e32 v117, v186
	v_add_f32_e32 v118, 1.0, v118
	v_rcp_f32_e32 v121, v118
	v_mul_f32_e32 v118, v186, v153
	v_pk_fma_f32 v[116:117], v[116:117], v[152:153], v[118:119] op_sel_hi:[1,1,0]
	v_rcp_f32_e32 v110, v110
	v_mul_f32_e32 v121, v212, v121
	v_exp_f32_e32 v243, v121
	v_fmamk_f32 v104, v104, 0xbfb8aa3b, v210
	v_exp_f32_e32 v104, v104
	v_fmamk_f32 v111, v111, 0xbfb8aa3b, v215
	v_fma_f32 v117, -v243, v243, 1.0
	v_sqrt_f32_e32 v118, v117
	v_fmamk_f32 v117, v119, 0xbfb8aa3b, v217
	v_exp_f32_e32 v121, v117
	v_exp_f32_e32 v123, v111
	v_mul_f32_e32 v118, v110, v118
	v_add_f32_e32 v104, 1.0, v104
	v_add_f32_e32 v110, 1.0, v121
	v_rcp_f32_e32 v121, v110
	v_mov_b32_e32 v119, v188
	v_mul_f32_e32 v110, v188, v243
	v_fmamk_f32 v100, v100, 0xbfb8aa3b, v208
	v_mul_f32_e32 v111, v213, v121
	v_exp_f32_e32 v245, v111
	v_rcp_f32_e32 v121, v104
	v_pk_fma_f32 v[110:111], v[118:119], v[242:243], v[110:111] op_sel_hi:[1,1,0]
	v_exp_f32_e32 v100, v100
	v_add_f32_e32 v111, 1.0, v123
	v_rcp_f32_e32 v118, v111
	v_fma_f32 v111, -v245, v245, 1.0
	v_sqrt_f32_e32 v119, v111
	v_mul_f32_e32 v121, v206, v121
	v_exp_f32_e32 v247, v121
	v_mul_f32_e32 v104, v190, v245
	v_mul_f32_e32 v118, v118, v119
	v_mov_b32_e32 v119, v190
	v_pk_fma_f32 v[118:119], v[118:119], v[244:245], v[104:105] op_sel_hi:[1,1,0]
	v_add_f32_e32 v100, 1.0, v100
	v_fma_f32 v104, -v247, v247, 1.0
	v_fmamk_f32 v105, v105, 0xbfb8aa3b, v211
	v_rcp_f32_e32 v100, v100
	v_sqrt_f32_e32 v104, v104
	v_exp_f32_e32 v121, v105
	v_fmamk_f32 v101, v101, 0xbfb8aa3b, v209
	v_exp_f32_e32 v123, v101
	v_mul_f32_e32 v104, v100, v104
	v_add_f32_e32 v100, 1.0, v121
	v_rcp_f32_e32 v121, v100
	v_lshlrev_b32_e32 v248, 16, v155
	v_and_b32_e32 v250, 0xffff0000, v155
	v_lshlrev_b32_e32 v246, 16, v154
	v_mul_f32_e32 v101, v207, v121
	v_exp_f32_e32 v155, v101
	v_mov_b32_e32 v105, v192
	v_mul_f32_e32 v100, v192, v247
	v_pk_fma_f32 v[100:101], v[104:105], v[246:247], v[100:101] op_sel_hi:[1,1,0]
	v_fmamk_f32 v102, v102, 0xbfb8aa3b, v202
	v_add_f32_e32 v101, 1.0, v123
	v_rcp_f32_e32 v104, v101
	v_fma_f32 v101, -v155, v155, 1.0
	v_sqrt_f32_e32 v105, v101
	v_fmamk_f32 v101, v106, 0xbfb8aa3b, v204
	v_exp_f32_e32 v106, v101
	v_and_b32_e32 v154, 0xffff0000, v154
	v_mul_f32_e32 v104, v104, v105
	v_mov_b32_e32 v105, v194
	v_add_f32_e32 v106, 1.0, v106
	v_rcp_f32_e32 v106, v106
	v_exp_f32_e32 v121, v102
	v_mul_f32_e32 v102, v194, v155
	v_pk_fma_f32 v[104:105], v[104:105], v[154:155], v[102:103] op_sel_hi:[1,1,0]
	v_fmamk_f32 v103, v103, 0xbfb8aa3b, v203
	v_mul_f32_e32 v105, v200, v106
	v_exp_f32_e32 v249, v105
	v_fmamk_f32 v105, v107, 0xbfb8aa3b, v205
	v_exp_f32_e32 v106, v105
	v_add_f32_e32 v102, 1.0, v121
	v_fma_f32 v105, -v249, v249, 1.0
	v_rcp_f32_e32 v102, v102
	v_add_f32_e32 v106, 1.0, v106
	v_sqrt_f32_e32 v107, v105
	v_rcp_f32_e32 v106, v106
	v_mul_f32_e32 v109, v136, v241
	v_mul_f32_e32 v117, v128, v153
	v_mul_f32_e32 v102, v102, v107
	v_exp_f32_e32 v107, v103
	v_mul_f32_e32 v103, v201, v106
	v_exp_f32_e32 v251, v103
	v_mov_b32_e32 v103, v196
	v_add_f32_e32 v106, 1.0, v107
	v_rcp_f32_e32 v107, v106
	v_fma_f32 v106, -v251, v251, 1.0
	v_sqrt_f32_e32 v121, v106
	v_mul_f32_e32 v106, v196, v249
	v_pk_fma_f32 v[102:103], v[102:103], v[248:249], v[106:107] op_sel_hi:[1,1,0]
	v_mul_f32_e32 v152, v198, v251
	v_mul_f32_e32 v106, v107, v121
	v_mov_b32_e32 v107, v198
	v_pk_fma_f32 v[106:107], v[106:107], v[250:251], v[152:153] op_sel_hi:[1,1,0]
	v_mul_f32_e32 v111, v138, v243
	v_mul_f32_e32 v119, v130, v245
	v_mul_f32_e32 v101, v124, v247
	v_mul_f32_e32 v105, v120, v155
	v_mul_f32_e32 v103, v122, v249
	v_mul_f32_e32 v107, v126, v251
	v_fmamk_f32 v96, v96, 0xbfb8aa3b, v222
	v_exp_f32_e32 v96, v96
	v_fmamk_f32 v88, v88, 0xbfb8aa3b, v220
	v_exp_f32_e32 v88, v88
	v_fmamk_f32 v97, v97, 0xbfb8aa3b, v223
	v_add_f32_e32 v96, 1.0, v96
	v_rcp_f32_e32 v96, v96
	v_add_f32_e32 v88, 1.0, v88
	v_rcp_f32_e32 v88, v88
	v_exp_f32_e32 v121, v97
	v_mul_f32_e32 v96, v218, v96
	v_exp_f32_e32 v153, v96
	v_fmamk_f32 v89, v89, 0xbfb8aa3b, v221
	v_exp_f32_e32 v123, v89
	v_lshlrev_b32_e32 v154, 16, v149
	v_fma_f32 v96, -v153, v153, 1.0
	v_sqrt_f32_e32 v96, v96
	v_and_b32_e32 v240, 0xffff0000, v149
	v_lshlrev_b32_e32 v152, 16, v148
	v_mov_b32_e32 v97, v108
	v_mul_f32_e32 v96, v88, v96
	v_add_f32_e32 v88, 1.0, v121
	v_rcp_f32_e32 v121, v88
	v_mul_f32_e32 v88, v108, v153
	v_fmamk_f32 v90, v90, 0xbfb8aa3b, v214
	v_exp_f32_e32 v90, v90
	v_mul_f32_e32 v89, v219, v121
	v_exp_f32_e32 v149, v89
	v_pk_fma_f32 v[88:89], v[96:97], v[152:153], v[88:89] op_sel_hi:[1,1,0]
	v_and_b32_e32 v148, 0xffff0000, v148
	v_add_f32_e32 v89, 1.0, v123
	v_rcp_f32_e32 v96, v89
	v_fma_f32 v89, -v149, v149, 1.0
	v_sqrt_f32_e32 v97, v89
	v_fmamk_f32 v89, v98, 0xbfb8aa3b, v216
	v_exp_f32_e32 v98, v89
	v_add_f32_e32 v90, 1.0, v90
	v_mul_f32_e32 v96, v96, v97
	v_mov_b32_e32 v97, v116
	v_add_f32_e32 v98, 1.0, v98
	v_rcp_f32_e32 v121, v98
	v_mul_f32_e32 v98, v116, v149
	v_pk_fma_f32 v[96:97], v[96:97], v[148:149], v[98:99] op_sel_hi:[1,1,0]
	v_rcp_f32_e32 v90, v90
	v_mul_f32_e32 v121, v212, v121
	v_exp_f32_e32 v155, v121
	v_fmamk_f32 v84, v84, 0xbfb8aa3b, v210
	v_exp_f32_e32 v84, v84
	v_fmamk_f32 v91, v91, 0xbfb8aa3b, v215
	v_fma_f32 v97, -v155, v155, 1.0
	v_sqrt_f32_e32 v98, v97
	v_fmamk_f32 v97, v99, 0xbfb8aa3b, v217
	v_exp_f32_e32 v121, v97
	v_exp_f32_e32 v123, v91
	v_mul_f32_e32 v98, v90, v98
	v_add_f32_e32 v84, 1.0, v84
	v_add_f32_e32 v90, 1.0, v121
	v_rcp_f32_e32 v121, v90
	v_mov_b32_e32 v99, v110
	v_mul_f32_e32 v90, v110, v155
	v_fmamk_f32 v80, v80, 0xbfb8aa3b, v208
	v_mul_f32_e32 v91, v213, v121
	v_exp_f32_e32 v241, v91
	v_rcp_f32_e32 v121, v84
	v_pk_fma_f32 v[90:91], v[98:99], v[154:155], v[90:91] op_sel_hi:[1,1,0]
	v_exp_f32_e32 v80, v80
	v_add_f32_e32 v91, 1.0, v123
	v_rcp_f32_e32 v98, v91
	v_fma_f32 v91, -v241, v241, 1.0
	v_sqrt_f32_e32 v99, v91
	v_mul_f32_e32 v121, v206, v121
	v_exp_f32_e32 v243, v121
	v_mul_f32_e32 v84, v118, v241
	v_mul_f32_e32 v98, v98, v99
	v_mov_b32_e32 v99, v118
	v_pk_fma_f32 v[98:99], v[98:99], v[240:241], v[84:85] op_sel_hi:[1,1,0]
	v_add_f32_e32 v80, 1.0, v80
	v_fma_f32 v84, -v243, v243, 1.0
	v_fmamk_f32 v85, v85, 0xbfb8aa3b, v211
	v_rcp_f32_e32 v80, v80
	v_sqrt_f32_e32 v84, v84
	v_exp_f32_e32 v121, v85
	v_fmamk_f32 v81, v81, 0xbfb8aa3b, v209
	v_exp_f32_e32 v123, v81
	v_mul_f32_e32 v84, v80, v84
	v_add_f32_e32 v80, 1.0, v121
	v_rcp_f32_e32 v121, v80
	v_lshlrev_b32_e32 v244, 16, v151
	v_and_b32_e32 v246, 0xffff0000, v151
	v_lshlrev_b32_e32 v242, 16, v150
	v_mul_f32_e32 v81, v207, v121
	v_exp_f32_e32 v151, v81
	v_mov_b32_e32 v85, v100
	v_mul_f32_e32 v80, v100, v243
	v_pk_fma_f32 v[80:81], v[84:85], v[242:243], v[80:81] op_sel_hi:[1,1,0]
	v_fmamk_f32 v82, v82, 0xbfb8aa3b, v202
	v_add_f32_e32 v81, 1.0, v123
	v_rcp_f32_e32 v84, v81
	v_fma_f32 v81, -v151, v151, 1.0
	v_sqrt_f32_e32 v85, v81
	v_fmamk_f32 v81, v86, 0xbfb8aa3b, v204
	v_exp_f32_e32 v86, v81
	v_and_b32_e32 v150, 0xffff0000, v150
	v_mul_f32_e32 v84, v84, v85
	v_mov_b32_e32 v85, v104
	v_add_f32_e32 v86, 1.0, v86
	v_rcp_f32_e32 v86, v86
	v_exp_f32_e32 v121, v82
	v_mul_f32_e32 v82, v104, v151
	v_pk_fma_f32 v[84:85], v[84:85], v[150:151], v[82:83] op_sel_hi:[1,1,0]
	v_fmamk_f32 v83, v83, 0xbfb8aa3b, v203
	v_mul_f32_e32 v85, v200, v86
	v_exp_f32_e32 v245, v85
	v_fmamk_f32 v85, v87, 0xbfb8aa3b, v205
	v_exp_f32_e32 v86, v85
	v_add_f32_e32 v82, 1.0, v121
	v_fma_f32 v85, -v245, v245, 1.0
	v_rcp_f32_e32 v82, v82
	v_add_f32_e32 v86, 1.0, v86
	v_sqrt_f32_e32 v87, v85
	v_rcp_f32_e32 v86, v86
	v_mul_f32_e32 v89, v153, v109
	v_mul_f32_e32 v97, v149, v117
	v_mul_f32_e32 v82, v82, v87
	v_exp_f32_e32 v87, v83
	v_mul_f32_e32 v83, v201, v86
	v_exp_f32_e32 v247, v83
	v_mov_b32_e32 v83, v102
	v_add_f32_e32 v86, 1.0, v87
	v_rcp_f32_e32 v87, v86
	v_fma_f32 v86, -v247, v247, 1.0
	v_sqrt_f32_e32 v121, v86
	v_mul_f32_e32 v86, v102, v245
	v_pk_fma_f32 v[82:83], v[82:83], v[244:245], v[86:87] op_sel_hi:[1,1,0]
	v_mul_f32_e32 v148, v106, v247
	v_mul_f32_e32 v86, v87, v121
	v_mov_b32_e32 v87, v106
	v_pk_fma_f32 v[86:87], v[86:87], v[246:247], v[148:149] op_sel_hi:[1,1,0]
	v_mul_f32_e32 v91, v155, v111
	v_mul_f32_e32 v99, v241, v119
	v_mul_f32_e32 v81, v243, v101
	v_mul_f32_e32 v85, v151, v105
	v_mul_f32_e32 v83, v245, v103
	v_mul_f32_e32 v87, v247, v107
	v_fmamk_f32 v76, v76, 0xbfb8aa3b, v222
	v_exp_f32_e32 v76, v76
	v_fmamk_f32 v72, v72, 0xbfb8aa3b, v220
	v_exp_f32_e32 v72, v72
	v_fmamk_f32 v77, v77, 0xbfb8aa3b, v223
	v_add_f32_e32 v76, 1.0, v76
	v_rcp_f32_e32 v76, v76
	v_add_f32_e32 v72, 1.0, v72
	v_rcp_f32_e32 v72, v72
	v_exp_f32_e32 v121, v77
	v_mul_f32_e32 v76, v218, v76
	v_exp_f32_e32 v149, v76
	v_fmamk_f32 v73, v73, 0xbfb8aa3b, v221
	v_exp_f32_e32 v123, v73
	v_lshlrev_b32_e32 v150, 16, v145
	v_fma_f32 v76, -v149, v149, 1.0
	v_sqrt_f32_e32 v76, v76
	v_and_b32_e32 v152, 0xffff0000, v145
	v_lshlrev_b32_e32 v148, 16, v144
	v_mov_b32_e32 v77, v88
	v_mul_f32_e32 v76, v72, v76
	v_add_f32_e32 v72, 1.0, v121
	v_rcp_f32_e32 v121, v72
	v_mul_f32_e32 v72, v88, v149
	v_fmamk_f32 v74, v74, 0xbfb8aa3b, v214
	v_exp_f32_e32 v74, v74
	v_mul_f32_e32 v73, v219, v121
	v_exp_f32_e32 v145, v73
	v_pk_fma_f32 v[72:73], v[76:77], v[148:149], v[72:73] op_sel_hi:[1,1,0]
	v_and_b32_e32 v144, 0xffff0000, v144
	v_add_f32_e32 v73, 1.0, v123
	v_rcp_f32_e32 v76, v73
	v_fma_f32 v73, -v145, v145, 1.0
	v_sqrt_f32_e32 v77, v73
	v_fmamk_f32 v73, v78, 0xbfb8aa3b, v216
	v_exp_f32_e32 v78, v73
	v_add_f32_e32 v74, 1.0, v74
	v_mul_f32_e32 v76, v76, v77
	v_mov_b32_e32 v77, v96
	v_add_f32_e32 v78, 1.0, v78
	v_rcp_f32_e32 v121, v78
	v_mul_f32_e32 v78, v96, v145
	v_pk_fma_f32 v[76:77], v[76:77], v[144:145], v[78:79] op_sel_hi:[1,1,0]
	v_rcp_f32_e32 v74, v74
	v_mul_f32_e32 v121, v212, v121
	v_exp_f32_e32 v151, v121
	v_fmamk_f32 v68, v68, 0xbfb8aa3b, v210
	v_exp_f32_e32 v68, v68
	v_fmamk_f32 v75, v75, 0xbfb8aa3b, v215
	v_fma_f32 v77, -v151, v151, 1.0
	v_sqrt_f32_e32 v78, v77
	v_fmamk_f32 v77, v79, 0xbfb8aa3b, v217
	v_exp_f32_e32 v121, v77
	v_exp_f32_e32 v123, v75
	v_mul_f32_e32 v78, v74, v78
	v_add_f32_e32 v68, 1.0, v68
	v_add_f32_e32 v74, 1.0, v121
	v_rcp_f32_e32 v121, v74
	v_mov_b32_e32 v79, v90
	v_mul_f32_e32 v74, v90, v151
	v_fmamk_f32 v64, v64, 0xbfb8aa3b, v208
	v_mul_f32_e32 v75, v213, v121
	v_exp_f32_e32 v153, v75
	v_rcp_f32_e32 v121, v68
	v_pk_fma_f32 v[74:75], v[78:79], v[150:151], v[74:75] op_sel_hi:[1,1,0]
	v_exp_f32_e32 v64, v64
	v_add_f32_e32 v75, 1.0, v123
	v_rcp_f32_e32 v78, v75
	v_fma_f32 v75, -v153, v153, 1.0
	v_sqrt_f32_e32 v79, v75
	v_mul_f32_e32 v121, v206, v121
	v_exp_f32_e32 v155, v121
	v_mul_f32_e32 v68, v98, v153
	v_mul_f32_e32 v78, v78, v79
	v_mov_b32_e32 v79, v98
	v_pk_fma_f32 v[78:79], v[78:79], v[152:153], v[68:69] op_sel_hi:[1,1,0]
	v_add_f32_e32 v64, 1.0, v64
	v_fma_f32 v68, -v155, v155, 1.0
	v_fmamk_f32 v69, v69, 0xbfb8aa3b, v211
	v_rcp_f32_e32 v64, v64
	v_sqrt_f32_e32 v68, v68
	v_exp_f32_e32 v121, v69
	v_fmamk_f32 v65, v65, 0xbfb8aa3b, v209
	v_exp_f32_e32 v123, v65
	v_mul_f32_e32 v68, v64, v68
	v_add_f32_e32 v64, 1.0, v121
	v_rcp_f32_e32 v121, v64
	v_lshlrev_b32_e32 v240, 16, v147
	v_and_b32_e32 v242, 0xffff0000, v147
	v_lshlrev_b32_e32 v154, 16, v146
	v_mul_f32_e32 v65, v207, v121
	v_exp_f32_e32 v147, v65
	v_mov_b32_e32 v69, v80
	v_mul_f32_e32 v64, v80, v155
	v_pk_fma_f32 v[64:65], v[68:69], v[154:155], v[64:65] op_sel_hi:[1,1,0]
	v_fmamk_f32 v66, v66, 0xbfb8aa3b, v202
	v_add_f32_e32 v65, 1.0, v123
	v_rcp_f32_e32 v68, v65
	v_fma_f32 v65, -v147, v147, 1.0
	v_sqrt_f32_e32 v69, v65
	v_fmamk_f32 v65, v70, 0xbfb8aa3b, v204
	v_exp_f32_e32 v70, v65
	v_and_b32_e32 v146, 0xffff0000, v146
	v_mul_f32_e32 v68, v68, v69
	v_mov_b32_e32 v69, v84
	v_add_f32_e32 v70, 1.0, v70
	v_rcp_f32_e32 v70, v70
	v_exp_f32_e32 v121, v66
	v_mul_f32_e32 v66, v84, v147
	v_pk_fma_f32 v[68:69], v[68:69], v[146:147], v[66:67] op_sel_hi:[1,1,0]
	v_fmamk_f32 v67, v67, 0xbfb8aa3b, v203
	v_mul_f32_e32 v69, v200, v70
	v_exp_f32_e32 v241, v69
	v_fmamk_f32 v69, v71, 0xbfb8aa3b, v205
	v_exp_f32_e32 v70, v69
	v_add_f32_e32 v66, 1.0, v121
	v_fma_f32 v69, -v241, v241, 1.0
	v_rcp_f32_e32 v66, v66
	v_add_f32_e32 v70, 1.0, v70
	v_sqrt_f32_e32 v71, v69
	v_rcp_f32_e32 v70, v70
	v_mul_f32_e32 v73, v149, v89
	v_mul_f32_e32 v77, v145, v97
	v_mul_f32_e32 v66, v66, v71
	v_exp_f32_e32 v71, v67
	v_mul_f32_e32 v67, v201, v70
	v_exp_f32_e32 v243, v67
	v_mov_b32_e32 v67, v82
	v_add_f32_e32 v70, 1.0, v71
	v_rcp_f32_e32 v71, v70
	v_fma_f32 v70, -v243, v243, 1.0
	v_sqrt_f32_e32 v121, v70
	v_mul_f32_e32 v70, v82, v241
	v_pk_fma_f32 v[66:67], v[66:67], v[240:241], v[70:71] op_sel_hi:[1,1,0]
	v_mul_f32_e32 v144, v86, v243
	v_mul_f32_e32 v70, v71, v121
	v_mov_b32_e32 v71, v86
	v_pk_fma_f32 v[70:71], v[70:71], v[242:243], v[144:145] op_sel_hi:[1,1,0]
	v_mul_f32_e32 v75, v151, v91
	v_mul_f32_e32 v79, v153, v99
	v_mul_f32_e32 v65, v155, v81
	v_mul_f32_e32 v69, v147, v85
	v_mul_f32_e32 v67, v241, v83
	v_mul_f32_e32 v71, v243, v87
	v_fmamk_f32 v60, v60, 0xbfb8aa3b, v222
	v_exp_f32_e32 v60, v60
	v_fmamk_f32 v56, v56, 0xbfb8aa3b, v220
	v_exp_f32_e32 v56, v56
	v_fmamk_f32 v61, v61, 0xbfb8aa3b, v223
	v_add_f32_e32 v60, 1.0, v60
	v_rcp_f32_e32 v60, v60
	v_add_f32_e32 v56, 1.0, v56
	v_rcp_f32_e32 v56, v56
	v_exp_f32_e32 v121, v61
	v_mul_f32_e32 v60, v218, v60
	v_exp_f32_e32 v145, v60
	v_fmamk_f32 v57, v57, 0xbfb8aa3b, v221
	v_exp_f32_e32 v123, v57
	v_lshlrev_b32_e32 v146, 16, v141
	v_fma_f32 v60, -v145, v145, 1.0
	v_sqrt_f32_e32 v60, v60
	v_and_b32_e32 v148, 0xffff0000, v141
	v_lshlrev_b32_e32 v144, 16, v140
	v_mov_b32_e32 v61, v72
	v_mul_f32_e32 v60, v56, v60
	v_add_f32_e32 v56, 1.0, v121
	v_rcp_f32_e32 v121, v56
	v_mul_f32_e32 v56, v72, v145
	v_fmamk_f32 v58, v58, 0xbfb8aa3b, v214
	v_exp_f32_e32 v58, v58
	v_mul_f32_e32 v57, v219, v121
	v_exp_f32_e32 v141, v57
	v_pk_fma_f32 v[56:57], v[60:61], v[144:145], v[56:57] op_sel_hi:[1,1,0]
	v_and_b32_e32 v140, 0xffff0000, v140
	v_add_f32_e32 v57, 1.0, v123
	v_rcp_f32_e32 v60, v57
	v_fma_f32 v57, -v141, v141, 1.0
	v_sqrt_f32_e32 v61, v57
	v_fmamk_f32 v57, v62, 0xbfb8aa3b, v216
	v_exp_f32_e32 v62, v57
	v_add_f32_e32 v58, 1.0, v58
	v_mul_f32_e32 v60, v60, v61
	v_mov_b32_e32 v61, v76
	v_add_f32_e32 v62, 1.0, v62
	v_rcp_f32_e32 v121, v62
	v_mul_f32_e32 v62, v76, v141
	v_pk_fma_f32 v[60:61], v[60:61], v[140:141], v[62:63] op_sel_hi:[1,1,0]
	v_rcp_f32_e32 v58, v58
	v_mul_f32_e32 v121, v212, v121
	v_exp_f32_e32 v147, v121
	v_fmamk_f32 v52, v52, 0xbfb8aa3b, v210
	v_exp_f32_e32 v52, v52
	v_fmamk_f32 v59, v59, 0xbfb8aa3b, v215
	v_fma_f32 v61, -v147, v147, 1.0
	v_sqrt_f32_e32 v62, v61
	v_fmamk_f32 v61, v63, 0xbfb8aa3b, v217
	v_exp_f32_e32 v121, v61
	v_exp_f32_e32 v123, v59
	v_mul_f32_e32 v62, v58, v62
	v_add_f32_e32 v52, 1.0, v52
	v_add_f32_e32 v58, 1.0, v121
	v_rcp_f32_e32 v121, v58
	v_mov_b32_e32 v63, v74
	v_mul_f32_e32 v58, v74, v147
	v_fmamk_f32 v48, v48, 0xbfb8aa3b, v208
	v_mul_f32_e32 v59, v213, v121
	v_exp_f32_e32 v149, v59
	v_rcp_f32_e32 v121, v52
	v_pk_fma_f32 v[58:59], v[62:63], v[146:147], v[58:59] op_sel_hi:[1,1,0]
	v_exp_f32_e32 v48, v48
	v_add_f32_e32 v59, 1.0, v123
	v_rcp_f32_e32 v62, v59
	v_fma_f32 v59, -v149, v149, 1.0
	v_sqrt_f32_e32 v63, v59
	v_mul_f32_e32 v121, v206, v121
	v_exp_f32_e32 v151, v121
	v_mul_f32_e32 v52, v78, v149
	v_mul_f32_e32 v62, v62, v63
	v_mov_b32_e32 v63, v78
	v_pk_fma_f32 v[62:63], v[62:63], v[148:149], v[52:53] op_sel_hi:[1,1,0]
	v_add_f32_e32 v48, 1.0, v48
	v_fma_f32 v52, -v151, v151, 1.0
	v_fmamk_f32 v53, v53, 0xbfb8aa3b, v211
	v_rcp_f32_e32 v48, v48
	v_sqrt_f32_e32 v52, v52
	v_exp_f32_e32 v121, v53
	v_fmamk_f32 v49, v49, 0xbfb8aa3b, v209
	v_exp_f32_e32 v123, v49
	v_mul_f32_e32 v52, v48, v52
	v_add_f32_e32 v48, 1.0, v121
	v_rcp_f32_e32 v121, v48
	v_lshlrev_b32_e32 v152, 16, v143
	v_and_b32_e32 v154, 0xffff0000, v143
	v_lshlrev_b32_e32 v150, 16, v142
	v_mul_f32_e32 v49, v207, v121
	v_exp_f32_e32 v143, v49
	v_mov_b32_e32 v53, v64
	v_mul_f32_e32 v48, v64, v151
	v_pk_fma_f32 v[48:49], v[52:53], v[150:151], v[48:49] op_sel_hi:[1,1,0]
	v_fmamk_f32 v50, v50, 0xbfb8aa3b, v202
	v_add_f32_e32 v49, 1.0, v123
	v_rcp_f32_e32 v52, v49
	v_fma_f32 v49, -v143, v143, 1.0
	v_sqrt_f32_e32 v53, v49
	v_fmamk_f32 v49, v54, 0xbfb8aa3b, v204
	v_exp_f32_e32 v54, v49
	v_and_b32_e32 v142, 0xffff0000, v142
	v_mul_f32_e32 v52, v52, v53
	v_mov_b32_e32 v53, v68
	v_add_f32_e32 v54, 1.0, v54
	v_rcp_f32_e32 v54, v54
	v_exp_f32_e32 v121, v50
	v_mul_f32_e32 v50, v68, v143
	v_pk_fma_f32 v[52:53], v[52:53], v[142:143], v[50:51] op_sel_hi:[1,1,0]
	v_fmamk_f32 v51, v51, 0xbfb8aa3b, v203
	v_mul_f32_e32 v53, v200, v54
	v_exp_f32_e32 v153, v53
	v_fmamk_f32 v53, v55, 0xbfb8aa3b, v205
	v_exp_f32_e32 v54, v53
	v_add_f32_e32 v50, 1.0, v121
	v_fma_f32 v53, -v153, v153, 1.0
	v_rcp_f32_e32 v50, v50
	v_add_f32_e32 v54, 1.0, v54
	v_sqrt_f32_e32 v55, v53
	v_rcp_f32_e32 v54, v54
	v_mul_f32_e32 v57, v145, v73
	v_mul_f32_e32 v61, v141, v77
	v_mul_f32_e32 v50, v50, v55
	v_exp_f32_e32 v55, v51
	v_mul_f32_e32 v51, v201, v54
	v_exp_f32_e32 v155, v51
	v_mov_b32_e32 v51, v66
	v_add_f32_e32 v54, 1.0, v55
	v_rcp_f32_e32 v55, v54
	v_fma_f32 v54, -v155, v155, 1.0
	v_sqrt_f32_e32 v121, v54
	v_mul_f32_e32 v54, v66, v153
	v_pk_fma_f32 v[50:51], v[50:51], v[152:153], v[54:55] op_sel_hi:[1,1,0]
	v_mul_f32_e32 v140, v70, v155
	v_mul_f32_e32 v54, v55, v121
	v_mov_b32_e32 v55, v70
	v_pk_fma_f32 v[54:55], v[54:55], v[154:155], v[140:141] op_sel_hi:[1,1,0]
	v_mul_f32_e32 v59, v147, v75
	v_mul_f32_e32 v63, v149, v79
	v_mul_f32_e32 v49, v151, v65
	v_mul_f32_e32 v53, v143, v69
	v_mul_f32_e32 v51, v153, v67
	v_mul_f32_e32 v55, v155, v71
	v_fmamk_f32 v44, v44, 0xbfb8aa3b, v222
	v_exp_f32_e32 v44, v44
	v_fmamk_f32 v40, v40, 0xbfb8aa3b, v220
	v_exp_f32_e32 v40, v40
	v_fmamk_f32 v45, v45, 0xbfb8aa3b, v223
	v_add_f32_e32 v44, 1.0, v44
	v_rcp_f32_e32 v44, v44
	v_add_f32_e32 v40, 1.0, v40
	v_rcp_f32_e32 v40, v40
	v_exp_f32_e32 v121, v45
	v_mul_f32_e32 v44, v218, v44
	v_exp_f32_e32 v141, v44
	v_fmamk_f32 v41, v41, 0xbfb8aa3b, v221
	v_exp_f32_e32 v123, v41
	v_lshlrev_b32_e32 v142, 16, v133
	v_fma_f32 v44, -v141, v141, 1.0
	v_sqrt_f32_e32 v44, v44
	v_and_b32_e32 v144, 0xffff0000, v133
	v_lshlrev_b32_e32 v140, 16, v132
	v_mov_b32_e32 v45, v56
	v_mul_f32_e32 v44, v40, v44
	v_add_f32_e32 v40, 1.0, v121
	v_rcp_f32_e32 v121, v40
	v_mul_f32_e32 v40, v56, v141
	v_fmamk_f32 v42, v42, 0xbfb8aa3b, v214
	v_exp_f32_e32 v42, v42
	v_mul_f32_e32 v41, v219, v121
	v_exp_f32_e32 v133, v41
	v_pk_fma_f32 v[40:41], v[44:45], v[140:141], v[40:41] op_sel_hi:[1,1,0]
	v_and_b32_e32 v132, 0xffff0000, v132
	v_add_f32_e32 v41, 1.0, v123
	v_rcp_f32_e32 v44, v41
	v_fma_f32 v41, -v133, v133, 1.0
	v_sqrt_f32_e32 v45, v41
	v_fmamk_f32 v41, v46, 0xbfb8aa3b, v216
	v_exp_f32_e32 v46, v41
	v_add_f32_e32 v42, 1.0, v42
	v_mul_f32_e32 v44, v44, v45
	v_mov_b32_e32 v45, v60
	v_add_f32_e32 v46, 1.0, v46
	v_rcp_f32_e32 v121, v46
	v_mul_f32_e32 v46, v60, v133
	v_pk_fma_f32 v[44:45], v[44:45], v[132:133], v[46:47] op_sel_hi:[1,1,0]
	v_rcp_f32_e32 v42, v42
	v_mul_f32_e32 v121, v212, v121
	v_exp_f32_e32 v143, v121
	v_fmamk_f32 v36, v36, 0xbfb8aa3b, v210
	v_exp_f32_e32 v36, v36
	v_fmamk_f32 v43, v43, 0xbfb8aa3b, v215
	v_fma_f32 v45, -v143, v143, 1.0
	v_sqrt_f32_e32 v46, v45
	v_fmamk_f32 v45, v47, 0xbfb8aa3b, v217
	v_exp_f32_e32 v121, v45
	v_exp_f32_e32 v123, v43
	v_mul_f32_e32 v46, v42, v46
	v_add_f32_e32 v36, 1.0, v36
	v_add_f32_e32 v42, 1.0, v121
	v_rcp_f32_e32 v121, v42
	v_mov_b32_e32 v47, v58
	v_mul_f32_e32 v42, v58, v143
	v_fmamk_f32 v32, v32, 0xbfb8aa3b, v208
	v_mul_f32_e32 v43, v213, v121
	v_exp_f32_e32 v145, v43
	v_rcp_f32_e32 v121, v36
	v_pk_fma_f32 v[42:43], v[46:47], v[142:143], v[42:43] op_sel_hi:[1,1,0]
	v_exp_f32_e32 v32, v32
	v_add_f32_e32 v43, 1.0, v123
	v_rcp_f32_e32 v46, v43
	v_fma_f32 v43, -v145, v145, 1.0
	v_sqrt_f32_e32 v47, v43
	v_mul_f32_e32 v121, v206, v121
	v_exp_f32_e32 v147, v121
	v_mul_f32_e32 v36, v62, v145
	v_mul_f32_e32 v46, v46, v47
	v_mov_b32_e32 v47, v62
	v_pk_fma_f32 v[46:47], v[46:47], v[144:145], v[36:37] op_sel_hi:[1,1,0]
	v_add_f32_e32 v32, 1.0, v32
	v_fma_f32 v36, -v147, v147, 1.0
	v_fmamk_f32 v37, v37, 0xbfb8aa3b, v211
	v_rcp_f32_e32 v32, v32
	v_sqrt_f32_e32 v36, v36
	v_exp_f32_e32 v121, v37
	v_fmamk_f32 v33, v33, 0xbfb8aa3b, v209
	v_exp_f32_e32 v123, v33
	v_mul_f32_e32 v36, v32, v36
	v_add_f32_e32 v32, 1.0, v121
	v_rcp_f32_e32 v121, v32
	v_lshlrev_b32_e32 v148, 16, v135
	v_and_b32_e32 v150, 0xffff0000, v135
	v_lshlrev_b32_e32 v146, 16, v134
	v_mul_f32_e32 v33, v207, v121
	v_exp_f32_e32 v135, v33
	v_mov_b32_e32 v37, v48
	v_mul_f32_e32 v32, v48, v147
	v_pk_fma_f32 v[32:33], v[36:37], v[146:147], v[32:33] op_sel_hi:[1,1,0]
	v_fmamk_f32 v34, v34, 0xbfb8aa3b, v202
	v_add_f32_e32 v33, 1.0, v123
	v_rcp_f32_e32 v36, v33
	v_fma_f32 v33, -v135, v135, 1.0
	v_sqrt_f32_e32 v37, v33
	v_fmamk_f32 v33, v38, 0xbfb8aa3b, v204
	v_exp_f32_e32 v38, v33
	v_and_b32_e32 v134, 0xffff0000, v134
	v_mul_f32_e32 v36, v36, v37
	v_mov_b32_e32 v37, v52
	v_add_f32_e32 v38, 1.0, v38
	v_rcp_f32_e32 v38, v38
	v_exp_f32_e32 v121, v34
	v_mul_f32_e32 v34, v52, v135
	v_pk_fma_f32 v[36:37], v[36:37], v[134:135], v[34:35] op_sel_hi:[1,1,0]
	v_fmamk_f32 v35, v35, 0xbfb8aa3b, v203
	v_mul_f32_e32 v37, v200, v38
	v_exp_f32_e32 v149, v37
	v_fmamk_f32 v37, v39, 0xbfb8aa3b, v205
	v_exp_f32_e32 v38, v37
	v_add_f32_e32 v34, 1.0, v121
	v_fma_f32 v37, -v149, v149, 1.0
	v_rcp_f32_e32 v34, v34
	v_add_f32_e32 v38, 1.0, v38
	v_sqrt_f32_e32 v39, v37
	v_rcp_f32_e32 v38, v38
	v_mul_f32_e32 v41, v141, v57
	v_mul_f32_e32 v45, v133, v61
	v_mul_f32_e32 v34, v34, v39
	v_exp_f32_e32 v39, v35
	v_mul_f32_e32 v35, v201, v38
	v_exp_f32_e32 v151, v35
	v_mov_b32_e32 v35, v50
	v_add_f32_e32 v38, 1.0, v39
	v_rcp_f32_e32 v39, v38
	v_fma_f32 v38, -v151, v151, 1.0
	v_sqrt_f32_e32 v121, v38
	v_mul_f32_e32 v38, v50, v149
	v_pk_fma_f32 v[34:35], v[34:35], v[148:149], v[38:39] op_sel_hi:[1,1,0]
	v_mul_f32_e32 v132, v54, v151
	v_mul_f32_e32 v38, v39, v121
	v_mov_b32_e32 v39, v54
	v_pk_fma_f32 v[38:39], v[38:39], v[150:151], v[132:133] op_sel_hi:[1,1,0]
	v_mul_f32_e32 v43, v143, v59
	v_mul_f32_e32 v47, v145, v63
	v_mul_f32_e32 v33, v147, v49
	v_mul_f32_e32 v37, v135, v53
	v_mul_f32_e32 v35, v149, v51
	v_mul_f32_e32 v39, v151, v55
	v_fmamk_f32 v28, v28, 0xbfb8aa3b, v222
	v_lshlrev_b32_e32 v132, 16, v112
	v_and_b32_e32 v134, 0xffff0000, v112
	v_exp_f32_e32 v112, v28
	v_fmamk_f32 v29, v29, 0xbfb8aa3b, v223
	v_exp_f32_e32 v29, v29
	v_fmamk_f32 v24, v24, 0xbfb8aa3b, v220
	v_add_f32_e32 v112, 1.0, v112
	v_rcp_f32_e32 v112, v112
	v_add_f32_e32 v29, 1.0, v29
	v_rcp_f32_e32 v29, v29
	v_lshlrev_b32_e32 v28, 16, v113
	v_and_b32_e32 v140, 0xffff0000, v113
	v_exp_f32_e32 v113, v24
	v_mul_f32_e32 v24, v218, v112
	v_exp_f32_e32 v133, v24
	v_fmamk_f32 v25, v25, 0xbfb8aa3b, v221
	v_mul_f32_e32 v29, v219, v29
	v_exp_f32_e32 v25, v25
	v_exp_f32_e32 v135, v29
	v_add_f32_e32 v112, 1.0, v113
	v_fma_f32 v113, -v133, v133, 1.0
	v_rcp_f32_e32 v112, v112
	v_sqrt_f32_e32 v113, v113
	v_add_f32_e32 v25, 1.0, v25
	v_fma_f32 v29, -v135, v135, 1.0
	v_fmamk_f32 v30, v30, 0xbfb8aa3b, v216
	v_rcp_f32_e32 v25, v25
	v_sqrt_f32_e32 v29, v29
	v_exp_f32_e32 v30, v30
	v_lshlrev_b32_e32 v142, 16, v114
	v_and_b32_e32 v144, 0xffff0000, v114
	v_mul_f32_e32 v112, v112, v113
	v_mov_b32_e32 v113, v40
	v_mul_f32_e32 v114, v40, v133
	v_pk_fma_f32 v[112:113], v[112:113], v[132:133], v[114:115] op_sel_hi:[1,1,0]
	v_mul_f32_e32 v114, v25, v29
	v_add_f32_e32 v25, 1.0, v30
	v_rcp_f32_e32 v25, v25
	v_fmamk_f32 v26, v26, 0xbfb8aa3b, v214
	v_exp_f32_e32 v26, v26
	v_lshlrev_b32_e32 v24, 16, v115
	v_mul_f32_e32 v25, v212, v25
	v_exp_f32_e32 v29, v25
	v_and_b32_e32 v148, 0xffff0000, v115
	v_mov_b32_e32 v115, v44
	v_mul_f32_e32 v30, v44, v135
	v_pk_fma_f32 v[114:115], v[114:115], v[134:135], v[30:31] op_sel_hi:[1,1,0]
	v_add_f32_e32 v25, 1.0, v26
	v_fma_f32 v26, -v29, v29, 1.0
	v_fmamk_f32 v30, v31, 0xbfb8aa3b, v217
	v_rcp_f32_e32 v25, v25
	v_sqrt_f32_e32 v26, v26
	v_exp_f32_e32 v121, v30
	v_fmamk_f32 v27, v27, 0xbfb8aa3b, v215
	v_exp_f32_e32 v27, v27
	v_mul_f32_e32 v30, v25, v26
	v_add_f32_e32 v25, 1.0, v121
	v_rcp_f32_e32 v25, v25
	v_mov_b32_e32 v31, v42
	v_mul_f32_e32 v26, v42, v29
	v_fmamk_f32 v20, v20, 0xbfb8aa3b, v210
	v_mul_f32_e32 v25, v213, v25
	v_exp_f32_e32 v141, v25
	v_mul_f32_e32 v113, v133, v41
	v_pk_fma_f32 v[132:133], v[30:31], v[28:29], v[26:27] op_sel_hi:[1,1,0]
	v_add_f32_e32 v25, 1.0, v27
	v_fma_f32 v26, -v141, v141, 1.0
	v_exp_f32_e32 v20, v20
	v_rcp_f32_e32 v25, v25
	v_sqrt_f32_e32 v26, v26
	v_fmamk_f32 v16, v16, 0xbfb8aa3b, v208
	v_add_f32_e32 v20, 1.0, v20
	v_exp_f32_e32 v16, v16
	v_mul_f32_e32 v26, v25, v26
	v_rcp_f32_e32 v25, v20
	v_mov_b32_e32 v27, v46
	v_mul_f32_e32 v20, v46, v141
	v_mul_f32_e32 v115, v135, v45
	v_mul_f32_e32 v25, v206, v25
	v_exp_f32_e32 v143, v25
	v_pk_fma_f32 v[134:135], v[26:27], v[140:141], v[20:21] op_sel_hi:[1,1,0]
	v_add_f32_e32 v16, 1.0, v16
	v_fmamk_f32 v21, v21, 0xbfb8aa3b, v211
	v_fma_f32 v20, -v143, v143, 1.0
	v_rcp_f32_e32 v16, v16
	v_sqrt_f32_e32 v20, v20
	v_exp_f32_e32 v25, v21
	v_fmamk_f32 v17, v17, 0xbfb8aa3b, v209
	v_exp_f32_e32 v17, v17
	v_mul_f32_e32 v20, v16, v20
	v_add_f32_e32 v16, 1.0, v25
	v_rcp_f32_e32 v25, v16
	v_mov_b32_e32 v21, v32
	v_mul_f32_e32 v16, v32, v143
	v_mul_f32_e32 v123, v141, v47
	v_mul_f32_e32 v25, v207, v25
	v_exp_f32_e32 v145, v25
	v_pk_fma_f32 v[140:141], v[20:21], v[142:143], v[16:17] op_sel_hi:[1,1,0]
	v_fmamk_f32 v20, v22, 0xbfb8aa3b, v204
	v_exp_f32_e32 v20, v20
	v_add_f32_e32 v16, 1.0, v17
	v_fma_f32 v17, -v145, v145, 1.0
	v_rcp_f32_e32 v16, v16
	v_sqrt_f32_e32 v17, v17
	v_add_f32_e32 v20, 1.0, v20
	v_rcp_f32_e32 v20, v20
	v_fmamk_f32 v18, v18, 0xbfb8aa3b, v202
	v_mul_f32_e32 v16, v16, v17
	v_mov_b32_e32 v17, v36
	v_exp_f32_e32 v21, v18
	v_mul_f32_e32 v18, v36, v145
	v_mul_f32_e32 v125, v143, v33
	v_pk_fma_f32 v[142:143], v[16:17], v[144:145], v[18:19] op_sel_hi:[1,1,0]
	v_mul_f32_e32 v17, v200, v20
	v_exp_f32_e32 v25, v17
	v_fmamk_f32 v17, v23, 0xbfb8aa3b, v205
	v_exp_f32_e32 v17, v17
	v_add_f32_e32 v16, 1.0, v21
	v_fma_f32 v18, -v25, v25, 1.0
	v_rcp_f32_e32 v16, v16
	v_sqrt_f32_e32 v18, v18
	v_add_f32_e32 v17, 1.0, v17
	v_rcp_f32_e32 v17, v17
	v_mul_f32_e32 v127, v145, v37
	v_mul_f32_e32 v16, v16, v18
	v_fmamk_f32 v18, v19, 0xbfb8aa3b, v203
	v_exp_f32_e32 v18, v18
	v_mul_f32_e32 v17, v201, v17
	v_exp_f32_e32 v149, v17
	v_mov_b32_e32 v17, v34
	v_add_f32_e32 v18, 1.0, v18
	v_rcp_f32_e32 v19, v18
	v_fma_f32 v18, -v149, v149, 1.0
	v_sqrt_f32_e32 v20, v18
	v_mul_f32_e32 v18, v34, v25
	v_pk_fma_f32 v[144:145], v[16:17], v[24:25], v[18:19] op_sel_hi:[1,1,0]
	v_mov_b32_e32 v17, v38
	v_mul_f32_e32 v16, v19, v20
	v_mul_f32_e32 v18, v38, v149
	v_mul_f32_e32 v121, v29, v43
	v_mul_f32_e32 v129, v25, v35
	v_pk_fma_f32 v[146:147], v[16:17], v[148:149], v[18:19] op_sel_hi:[1,1,0]
	v_mul_f32_e32 v131, v149, v39
	v_fmamk_f32 v12, v12, 0xbfb8aa3b, v222
	v_exp_f32_e32 v17, v12
	v_fmamk_f32 v8, v8, 0xbfb8aa3b, v220
	v_fmac_f32_e32 v223, 0xbfb8aa3b, v13
	v_exp_f32_e32 v19, v8
	v_add_f32_e32 v17, 1.0, v17
	v_rcp_f32_e32 v17, v17
	v_exp_f32_e32 v13, v223
	v_add_f32_e32 v19, 1.0, v19
	v_rcp_f32_e32 v19, v19
	v_mul_f32_e32 v8, v218, v17
	v_exp_f32_e32 v17, v8
	v_add_f32_e32 v13, 1.0, v13
	v_rcp_f32_e32 v13, v13
	v_fmac_f32_e32 v221, 0xbfb8aa3b, v9
	v_fma_f32 v21, -v17, v17, 1.0
	v_sqrt_f32_e32 v21, v21
	v_mul_f32_e32 v13, v219, v13
	v_exp_f32_e32 v9, v221
	v_fmamk_f32 v14, v14, 0xbfb8aa3b, v216
	v_mul_f32_e32 v28, v19, v21
	v_exp_f32_e32 v19, v13
	v_add_f32_e32 v9, 1.0, v9
	v_rcp_f32_e32 v9, v9
	v_exp_f32_e32 v14, v14
	v_fma_f32 v13, -v19, v19, 1.0
	v_sqrt_f32_e32 v13, v13
	v_lshlrev_b32_e32 v16, 16, v92
	v_mov_b32_e32 v29, v112
	v_pk_mul_f32 v[28:29], v[28:29], v[16:17]
	v_mul_f32_e32 v16, v9, v13
	v_add_f32_e32 v9, 1.0, v14
	v_rcp_f32_e32 v9, v9
	v_fmamk_f32 v10, v10, 0xbfb8aa3b, v214
	v_exp_f32_e32 v10, v10
	v_and_b32_e32 v18, 0xffff0000, v92
	v_mul_f32_e32 v9, v212, v9
	v_exp_f32_e32 v13, v9
	v_mul_f32_e32 v135, v17, v113
	v_mov_b32_e32 v17, v114
	v_pk_mul_f32 v[16:17], v[16:17], v[18:19]
	v_add_f32_e32 v9, 1.0, v10
	v_fma_f32 v10, -v13, v13, 1.0
	v_fmac_f32_e32 v217, 0xbfb8aa3b, v15
	v_add_f32_e32 v137, v16, v17
	v_rcp_f32_e32 v9, v9
	v_sqrt_f32_e32 v10, v10
	v_exp_f32_e32 v16, v217
	v_fmamk_f32 v4, v4, 0xbfb8aa3b, v210
	v_exp_f32_e32 v4, v4
	v_mul_f32_e32 v14, v9, v10
	v_add_f32_e32 v9, 1.0, v16
	v_rcp_f32_e32 v9, v9
	v_add_f32_e32 v4, 1.0, v4
	v_fmac_f32_e32 v215, 0xbfb8aa3b, v11
	v_rcp_f32_e32 v4, v4
	v_mul_f32_e32 v9, v213, v9
	v_exp_f32_e32 v10, v215
	v_exp_f32_e32 v21, v9
	v_fmamk_f32 v0, v0, 0xbfb8aa3b, v208
	v_mul_f32_e32 v4, v206, v4
	v_add_f32_e32 v9, 1.0, v10
	v_fma_f32 v10, -v21, v21, 1.0
	v_exp_f32_e32 v0, v0
	v_exp_f32_e32 v23, v4
	v_rcp_f32_e32 v9, v9
	v_sqrt_f32_e32 v10, v10
	v_add_f32_e32 v0, 1.0, v0
	v_fma_f32 v4, -v23, v23, 1.0
	v_fmac_f32_e32 v211, 0xbfb8aa3b, v5
	v_mul_f32_e32 v10, v9, v10
	v_rcp_f32_e32 v0, v0
	v_sqrt_f32_e32 v4, v4
	v_exp_f32_e32 v9, v211
	v_lshlrev_b32_e32 v22, 16, v94
	v_mov_b32_e32 v5, v140
	v_mul_f32_e32 v4, v0, v4
	v_add_f32_e32 v0, 1.0, v9
	v_rcp_f32_e32 v0, v0
	v_fmac_f32_e32 v209, 0xbfb8aa3b, v1
	v_pk_mul_f32 v[4:5], v[4:5], v[22:23]
	v_exp_f32_e32 v1, v209
	v_mul_f32_e32 v0, v207, v0
	v_exp_f32_e32 v25, v0
	v_add_f32_e32 v147, v4, v5
	v_fmamk_f32 v4, v6, 0xbfb8aa3b, v204
	v_exp_f32_e32 v4, v4
	v_add_f32_e32 v0, 1.0, v1
	v_fma_f32 v1, -v25, v25, 1.0
	v_rcp_f32_e32 v0, v0
	v_sqrt_f32_e32 v1, v1
	v_add_f32_e32 v4, 1.0, v4
	v_rcp_f32_e32 v4, v4
	v_and_b32_e32 v24, 0xffff0000, v94
	v_mul_f32_e32 v0, v0, v1
	v_mov_b32_e32 v1, v142
	v_pk_mul_f32 v[0:1], v[0:1], v[24:25]
	v_fmac_f32_e32 v205, 0xbfb8aa3b, v7
	v_add_f32_e32 v187, v0, v1
	v_mul_f32_e32 v1, v200, v4
	v_fmamk_f32 v2, v2, 0xbfb8aa3b, v202
	v_exp_f32_e32 v9, v1
	v_exp_f32_e32 v1, v205
	v_exp_f32_e32 v2, v2
	v_fmac_f32_e32 v203, 0xbfb8aa3b, v3
	v_lshlrev_b32_e32 v8, 16, v95
	v_add_f32_e32 v1, 1.0, v1
	v_add_f32_e32 v0, 1.0, v2
	v_fma_f32 v2, -v9, v9, 1.0
	v_rcp_f32_e32 v1, v1
	v_rcp_f32_e32 v0, v0
	v_sqrt_f32_e32 v2, v2
	v_lshlrev_b32_e32 v12, 16, v93
	v_mul_f32_e32 v1, v201, v1
	v_exp_f32_e32 v27, v1
	v_mul_f32_e32 v0, v0, v2
	v_exp_f32_e32 v2, v203
	v_mov_b32_e32 v1, v144
	v_fma_f32 v3, -v27, v27, 1.0
	v_sqrt_f32_e32 v3, v3
	v_add_f32_e32 v2, 1.0, v2
	v_rcp_f32_e32 v2, v2
	v_pk_mul_f32 v[0:1], v[0:1], v[8:9]
	v_and_b32_e32 v20, 0xffff0000, v93
	v_and_b32_e32 v26, 0xffff0000, v95
	v_mov_b32_e32 v15, v132
	v_mov_b32_e32 v11, v134
	v_add_f32_e32 v193, v0, v1
	v_mul_f32_e32 v0, v2, v3
	v_mov_b32_e32 v1, v146
	v_pk_mul_f32 v[14:15], v[14:15], v[12:13]
	v_pk_mul_f32 v[10:11], v[10:11], v[20:21]
	v_pk_mul_f32 v[0:1], v[0:1], v[26:27]
	v_add_f32_e32 v133, v28, v29
	v_mul_f32_e32 v141, v19, v115
	v_add_f32_e32 v139, v14, v15
	v_mul_f32_e32 v143, v13, v121
	v_add_f32_e32 v145, v10, v11
	v_mul_f32_e32 v185, v21, v123
	v_mul_f32_e32 v189, v23, v125
	v_mul_f32_e32 v191, v25, v127
	v_mul_f32_e32 v197, v9, v129
	v_add_f32_e32 v195, v0, v1
	v_mul_f32_e32 v199, v27, v131
	v_mov_b32_e32 v0, v135
	v_mov_b32_e32 v17, v133
	v_mov_b32_e32 v2, v141
	v_mov_b32_e32 v19, v137
	v_mov_b32_e32 v4, v143
	v_mov_b32_e32 v21, v139
	v_mov_b32_e32 v6, v185
	v_mov_b32_e32 v23, v145
	v_mov_b32_e32 v8, v189
	v_mov_b32_e32 v25, v147
	v_mov_b32_e32 v10, v191
	v_mov_b32_e32 v27, v187
	v_mov_b32_e32 v12, v197
	v_mov_b32_e32 v31, v193
	v_mov_b32_e32 v14, v199
	v_mov_b32_e32 v205, v195
	v_fmac_f32_dpp v17, v17, v0 row_shr:1 row_mask:0xf bank_mask:0xf
	v_fmac_f32_dpp v19, v19, v2 row_shr:1 row_mask:0xf bank_mask:0xf
	v_fmac_f32_dpp v21, v21, v4 row_shr:1 row_mask:0xf bank_mask:0xf
	v_fmac_f32_dpp v23, v23, v6 row_shr:1 row_mask:0xf bank_mask:0xf
	v_fmac_f32_dpp v25, v25, v8 row_shr:1 row_mask:0xf bank_mask:0xf
	v_fmac_f32_dpp v27, v27, v10 row_shr:1 row_mask:0xf bank_mask:0xf
	v_fmac_f32_dpp v31, v31, v12 row_shr:1 row_mask:0xf bank_mask:0xf
	v_fmac_f32_dpp v205, v205, v14 row_shr:1 row_mask:0xf bank_mask:0xf
	v_mul_f32_dpp v0, v0, v0 row_shr:1 row_mask:0xf bank_mask:0xf
	v_mul_f32_dpp v2, v2, v2 row_shr:1 row_mask:0xf bank_mask:0xf
	v_mul_f32_dpp v4, v4, v4 row_shr:1 row_mask:0xf bank_mask:0xf
	v_mul_f32_dpp v6, v6, v6 row_shr:1 row_mask:0xf bank_mask:0xf
	v_mul_f32_dpp v8, v8, v8 row_shr:1 row_mask:0xf bank_mask:0xf
	v_mul_f32_dpp v10, v10, v10 row_shr:1 row_mask:0xf bank_mask:0xf
	v_mul_f32_dpp v12, v12, v12 row_shr:1 row_mask:0xf bank_mask:0xf
	v_mul_f32_dpp v14, v14, v14 row_shr:1 row_mask:0xf bank_mask:0xf
	v_fmac_f32_dpp v17, v17, v0 row_shr:2 row_mask:0xf bank_mask:0xf
	v_fmac_f32_dpp v19, v19, v2 row_shr:2 row_mask:0xf bank_mask:0xf
	v_fmac_f32_dpp v21, v21, v4 row_shr:2 row_mask:0xf bank_mask:0xf
	v_fmac_f32_dpp v23, v23, v6 row_shr:2 row_mask:0xf bank_mask:0xf
	v_fmac_f32_dpp v25, v25, v8 row_shr:2 row_mask:0xf bank_mask:0xf
	v_fmac_f32_dpp v27, v27, v10 row_shr:2 row_mask:0xf bank_mask:0xf
	v_fmac_f32_dpp v31, v31, v12 row_shr:2 row_mask:0xf bank_mask:0xf
	v_fmac_f32_dpp v205, v205, v14 row_shr:2 row_mask:0xf bank_mask:0xf
	v_mul_f32_dpp v0, v0, v0 row_shr:2 row_mask:0xf bank_mask:0xf
	v_mul_f32_dpp v2, v2, v2 row_shr:2 row_mask:0xf bank_mask:0xf
	v_mul_f32_dpp v4, v4, v4 row_shr:2 row_mask:0xf bank_mask:0xf
	v_mul_f32_dpp v6, v6, v6 row_shr:2 row_mask:0xf bank_mask:0xf
	v_mul_f32_dpp v8, v8, v8 row_shr:2 row_mask:0xf bank_mask:0xf
	v_mul_f32_dpp v10, v10, v10 row_shr:2 row_mask:0xf bank_mask:0xf
	v_mul_f32_dpp v12, v12, v12 row_shr:2 row_mask:0xf bank_mask:0xf
	v_mul_f32_dpp v14, v14, v14 row_shr:2 row_mask:0xf bank_mask:0xf
	v_fmac_f32_dpp v17, v17, v0 row_shr:4 row_mask:0xf bank_mask:0xf
	v_fmac_f32_dpp v19, v19, v2 row_shr:4 row_mask:0xf bank_mask:0xf
	v_fmac_f32_dpp v21, v21, v4 row_shr:4 row_mask:0xf bank_mask:0xf
	v_fmac_f32_dpp v23, v23, v6 row_shr:4 row_mask:0xf bank_mask:0xf
	v_fmac_f32_dpp v25, v25, v8 row_shr:4 row_mask:0xf bank_mask:0xf
	v_fmac_f32_dpp v27, v27, v10 row_shr:4 row_mask:0xf bank_mask:0xf
	v_fmac_f32_dpp v31, v31, v12 row_shr:4 row_mask:0xf bank_mask:0xf
	v_fmac_f32_dpp v205, v205, v14 row_shr:4 row_mask:0xf bank_mask:0xf
	v_mul_f32_dpp v0, v0, v0 row_shr:4 row_mask:0xf bank_mask:0xf
	v_mul_f32_dpp v2, v2, v2 row_shr:4 row_mask:0xf bank_mask:0xf
	v_mul_f32_dpp v4, v4, v4 row_shr:4 row_mask:0xf bank_mask:0xf
	v_mul_f32_dpp v6, v6, v6 row_shr:4 row_mask:0xf bank_mask:0xf
	v_mul_f32_dpp v8, v8, v8 row_shr:4 row_mask:0xf bank_mask:0xf
	v_mul_f32_dpp v10, v10, v10 row_shr:4 row_mask:0xf bank_mask:0xf
	v_mul_f32_dpp v12, v12, v12 row_shr:4 row_mask:0xf bank_mask:0xf
	v_mul_f32_dpp v14, v14, v14 row_shr:4 row_mask:0xf bank_mask:0xf
	v_mul_f32_dpp v1, v17, v0 row_shr:8 row_mask:0xf bank_mask:0xf bound_ctrl:1
	v_mul_f32_dpp v3, v19, v2 row_shr:8 row_mask:0xf bank_mask:0xf bound_ctrl:1
	v_mul_f32_dpp v5, v21, v4 row_shr:8 row_mask:0xf bank_mask:0xf bound_ctrl:1
	v_mul_f32_dpp v7, v23, v6 row_shr:8 row_mask:0xf bank_mask:0xf bound_ctrl:1
	v_mul_f32_dpp v9, v25, v8 row_shr:8 row_mask:0xf bank_mask:0xf bound_ctrl:1
	v_mul_f32_dpp v11, v27, v10 row_shr:8 row_mask:0xf bank_mask:0xf bound_ctrl:1
	v_mul_f32_dpp v13, v31, v12 row_shr:8 row_mask:0xf bank_mask:0xf bound_ctrl:1
	v_mul_f32_dpp v15, v205, v14 row_shr:8 row_mask:0xf bank_mask:0xf bound_ctrl:1
	v_mul_f32_dpp v0, v0, v0 row_shr:8 row_mask:0xf bank_mask:0xf
	v_mul_f32_dpp v2, v2, v2 row_shr:8 row_mask:0xf bank_mask:0xf
	v_mul_f32_dpp v4, v4, v4 row_shr:8 row_mask:0xf bank_mask:0xf
	v_mul_f32_dpp v6, v6, v6 row_shr:8 row_mask:0xf bank_mask:0xf
	v_mul_f32_dpp v8, v8, v8 row_shr:8 row_mask:0xf bank_mask:0xf
	v_mul_f32_dpp v10, v10, v10 row_shr:8 row_mask:0xf bank_mask:0xf
	v_mul_f32_dpp v12, v12, v12 row_shr:8 row_mask:0xf bank_mask:0xf
	v_mul_f32_dpp v14, v14, v14 row_shr:8 row_mask:0xf bank_mask:0xf
	v_add_f32_e32 v17, v1, v17
	v_add_f32_e32 v19, v3, v19
	v_add_f32_e32 v21, v5, v21
	v_add_f32_e32 v23, v7, v23
	v_add_f32_e32 v25, v9, v25
	v_add_f32_e32 v27, v11, v27
	v_add_f32_e32 v31, v13, v31
	v_add_f32_e32 v205, v15, v205
	v_mov_b32_e32 v93, 1.0
	v_mov_b32_e32 v95, 1.0
	v_mov_b32_e32 v149, 1.0
	v_mov_b32_e32 v151, 1.0
	v_mov_b32_e32 v153, 1.0
	v_mov_b32_e32 v155, 1.0
	v_mov_b32_e32 v201, 1.0
	v_mov_b32_e32 v203, 1.0
	v_lshlrev_b32_e32 v1, 6, v237
	v_cmp_eq_u32_e64 s[8:9], 15, v239
	v_mov_b32_dpp v93, v0 row_shr:1 row_mask:0xf bank_mask:0xf
	v_mov_b32_dpp v92, v17 row_shr:1 row_mask:0xf bank_mask:0xf bound_ctrl:1
	v_mov_b32_dpp v95, v2 row_shr:1 row_mask:0xf bank_mask:0xf
	v_mov_b32_dpp v94, v19 row_shr:1 row_mask:0xf bank_mask:0xf bound_ctrl:1
	v_mov_b32_dpp v149, v4 row_shr:1 row_mask:0xf bank_mask:0xf
	v_mov_b32_dpp v148, v21 row_shr:1 row_mask:0xf bank_mask:0xf bound_ctrl:1
	v_mov_b32_dpp v151, v6 row_shr:1 row_mask:0xf bank_mask:0xf
	v_mov_b32_dpp v150, v23 row_shr:1 row_mask:0xf bank_mask:0xf bound_ctrl:1
	v_mov_b32_dpp v153, v8 row_shr:1 row_mask:0xf bank_mask:0xf
	v_mov_b32_dpp v152, v25 row_shr:1 row_mask:0xf bank_mask:0xf bound_ctrl:1
	v_mov_b32_dpp v155, v10 row_shr:1 row_mask:0xf bank_mask:0xf
	v_mov_b32_dpp v154, v27 row_shr:1 row_mask:0xf bank_mask:0xf bound_ctrl:1
	v_mov_b32_dpp v201, v12 row_shr:1 row_mask:0xf bank_mask:0xf
	v_mov_b32_dpp v200, v31 row_shr:1 row_mask:0xf bank_mask:0xf bound_ctrl:1
	v_mov_b32_dpp v203, v14 row_shr:1 row_mask:0xf bank_mask:0xf
	v_mov_b32_dpp v202, v205 row_shr:1 row_mask:0xf bank_mask:0xf bound_ctrl:1
	s_and_b64 s[20:21], s[46:47], s[8:9]
	v_add_u32_e32 v171, s17, v1
	s_and_saveexec_b64 s[6:7], s[20:21]
	s_cbranch_execz .LBB0_466
	ds_write2_b32 v171, v0, v17 offset1:1
	ds_write2_b32 v171, v2, v19 offset0:2 offset1:3
	ds_write2_b32 v171, v4, v21 offset0:4 offset1:5
	ds_write2_b32 v171, v6, v23 offset0:6 offset1:7
	ds_write2_b32 v171, v8, v25 offset0:8 offset1:9
	ds_write2_b32 v171, v10, v27 offset0:10 offset1:11
	ds_write2_b32 v171, v12, v31 offset0:12 offset1:13
	ds_write2_b32 v171, v14, v205 offset0:14 offset1:15

.LBB0_487:
	s_or_b64 exec, exec, s[8:9]
	s_waitcnt lgkmcnt(0)
	v_mul_f32_e32 v9, v20, v151
	v_mul_f32_e32 v11, v18, v149
	v_mul_f32_e32 v13, v16, v95
	v_mul_f32_e32 v15, v28, v93
	v_mul_f32_e32 v1, v26, v201
	v_mul_f32_e32 v3, v24, v155
	v_mul_f32_e32 v5, v22, v153
	v_mul_f32_e32 v7, v30, v203
	v_fmac_f32_e32 v92, v29, v93
	v_fmac_f32_e32 v94, v17, v95
	v_fmac_f32_e32 v148, v19, v149
	v_fmac_f32_e32 v150, v21, v151
	v_fmac_f32_e32 v152, v23, v153
	v_fmac_f32_e32 v154, v25, v155
	v_fmac_f32_e32 v200, v27, v201
	v_fmac_f32_e32 v202, v31, v203
